# post phase cross-row software pipelining: next row's 24 loads issued into holding registers before the current row's compute
# speedup vs baseline: 1.0046x; 1.0046x over previous
.Lpost_nonext:
	v_lshlrev_b32_e32 v98, 16, v34
	v_mul_f32_e32 v100, 0xbfb8aa3b, v98
	v_exp_f32_e32 v100, v100
	v_and_b32_e32 v34, 0xffff0000, v34
	v_lshlrev_b32_e32 v99, 16, v35
	v_and_b32_e32 v35, 0xffff0000, v35
	v_add_f32_e32 v100, 1.0, v100
	v_lshlrev_b32_e32 v4, 16, v16
	v_and_b32_e32 v5, 0xffff0000, v16
	v_lshlrev_b32_e32 v6, 16, v22
	v_and_b32_e32 v7, 0xffff0000, v22
	v_pk_add_f32 v[4:5], v[4:5], v[6:7]
	v_lshlrev_b32_e32 v6, 16, v17
	v_and_b32_e32 v7, 0xffff0000, v17
	v_lshlrev_b32_e32 v12, 16, v23
	v_and_b32_e32 v13, 0xffff0000, v23
	v_pk_add_f32 v[6:7], v[6:7], v[12:13]
	v_add_f32_e32 v12, v4, v5
	v_add_f32_e32 v12, v6, v12
	v_add_f32_e32 v70, v7, v12
	v_lshlrev_b32_e32 v12, 16, v24
	v_and_b32_e32 v13, 0xffff0000, v24
	v_lshlrev_b32_e32 v16, 16, v26
	v_and_b32_e32 v17, 0xffff0000, v26
	v_pk_add_f32 v[80:81], v[12:13], v[16:17]
	v_lshlrev_b32_e32 v12, 16, v25
	v_and_b32_e32 v13, 0xffff0000, v25
	v_lshlrev_b32_e32 v16, 16, v27
	v_and_b32_e32 v17, 0xffff0000, v27
	v_pk_add_f32 v[78:79], v[12:13], v[16:17]
	v_add_f32_e32 v12, v80, v81
	v_add_f32_e32 v12, v78, v12
	v_add_f32_e32 v26, v79, v12
	v_lshlrev_b32_e32 v12, 16, v28
	v_and_b32_e32 v13, 0xffff0000, v28
	v_lshlrev_b32_e32 v16, 16, v30
	v_and_b32_e32 v17, 0xffff0000, v30
	v_pk_add_f32 v[64:65], v[12:13], v[16:17]
	v_lshlrev_b32_e32 v12, 16, v29
	v_and_b32_e32 v13, 0xffff0000, v29
	v_lshlrev_b32_e32 v16, 16, v31
	v_and_b32_e32 v17, 0xffff0000, v31
	v_pk_add_f32 v[66:67], v[12:13], v[16:17]
	v_add_f32_e32 v12, v64, v65
	v_add_f32_e32 v12, v66, v12
	v_add_f32_e32 v27, v67, v12
	v_lshlrev_b32_e32 v12, 16, v32
	v_and_b32_e32 v13, 0xffff0000, v32
	v_lshlrev_b32_e32 v16, 16, v38
	v_and_b32_e32 v17, 0xffff0000, v38
	v_pk_add_f32 v[60:61], v[12:13], v[16:17]
	v_lshlrev_b32_e32 v12, 16, v33
	s_waitcnt lgkmcnt(0)
	v_mov_b32_e32 v32, v26
	s_nop 1
	v_permlane32_swap_b32_e32 v32, v26
	s_nop 1
	v_add_f32_e32 v26, v26, v32
	v_and_b32_e32 v13, 0xffff0000, v33
	v_lshlrev_b32_e32 v16, 16, v39
	v_and_b32_e32 v17, 0xffff0000, v39
	v_pk_add_f32 v[58:59], v[12:13], v[16:17]
	v_add_f32_e32 v12, v60, v61
	v_add_f32_e32 v12, v58, v12
	v_add_f32_e32 v28, v59, v12
	v_lshlrev_b32_e32 v12, 16, v40
	v_and_b32_e32 v13, 0xffff0000, v40
	v_lshlrev_b32_e32 v16, 16, v46
	v_and_b32_e32 v17, 0xffff0000, v46
	s_waitcnt lgkmcnt(0)
	v_mov_b32_e32 v32, v27
	s_nop 1
	v_permlane32_swap_b32_e32 v32, v27
	s_nop 1
	v_add_f32_e32 v27, v27, v32
	v_pk_add_f32 v[44:45], v[12:13], v[16:17]
	v_lshlrev_b32_e32 v12, 16, v41
	v_and_b32_e32 v13, 0xffff0000, v41
	v_lshlrev_b32_e32 v16, 16, v47
	v_and_b32_e32 v17, 0xffff0000, v47
	v_pk_add_f32 v[46:47], v[12:13], v[16:17]
	v_add_f32_e32 v12, v44, v45
	v_add_f32_e32 v12, v46, v12
	v_add_f32_e32 v29, v47, v12
	v_lshlrev_b32_e32 v12, 16, v48
	v_and_b32_e32 v13, 0xffff0000, v48
	v_lshlrev_b32_e32 v16, 16, v50
	v_and_b32_e32 v17, 0xffff0000, v50
	s_waitcnt lgkmcnt(0)
	v_mov_b32_e32 v32, v28
	s_nop 1
	v_permlane32_swap_b32_e32 v32, v28
	s_nop 1
	v_add_f32_e32 v28, v28, v32
	v_pk_add_f32 v[40:41], v[12:13], v[16:17]
	v_lshlrev_b32_e32 v12, 16, v49
	v_and_b32_e32 v13, 0xffff0000, v49
	v_lshlrev_b32_e32 v16, 16, v51
	v_and_b32_e32 v17, 0xffff0000, v51
	v_pk_add_f32 v[38:39], v[12:13], v[16:17]
	v_add_f32_e32 v12, v40, v41
	v_add_f32_e32 v12, v38, v12
	v_add_f32_e32 v30, v39, v12
	v_lshlrev_b32_e32 v12, 16, v52
	v_and_b32_e32 v13, 0xffff0000, v52
	v_lshlrev_b32_e32 v16, 16, v54
	v_and_b32_e32 v17, 0xffff0000, v54
	s_waitcnt lgkmcnt(0)
	v_mov_b32_e32 v32, v29
	s_nop 1
	v_permlane32_swap_b32_e32 v32, v29
	s_nop 1
	v_add_f32_e32 v29, v29, v32
	v_pk_add_f32 v[22:23], v[12:13], v[16:17]
	v_lshlrev_b32_e32 v12, 16, v53
	v_and_b32_e32 v13, 0xffff0000, v53
	v_lshlrev_b32_e32 v16, 16, v55
	v_and_b32_e32 v17, 0xffff0000, v55
	v_pk_add_f32 v[24:25], v[12:13], v[16:17]
	v_add_f32_e32 v12, v22, v23
	v_add_f32_e32 v12, v24, v12
	v_add_f32_e32 v31, v25, v12
	v_lshlrev_b32_e32 v12, 16, v14
	v_and_b32_e32 v13, 0xffff0000, v14
	v_lshlrev_b32_e32 v16, 16, v68
	v_and_b32_e32 v17, 0xffff0000, v68
	s_waitcnt lgkmcnt(0)
	v_mov_b32_e32 v32, v30
	s_nop 1
	v_permlane32_swap_b32_e32 v32, v30
	s_nop 1
	v_add_f32_e32 v30, v30, v32
	v_pk_add_f32 v[16:17], v[12:13], v[16:17]
	v_lshlrev_b32_e32 v12, 16, v15
	v_and_b32_e32 v13, 0xffff0000, v15
	v_lshlrev_b32_e32 v14, 16, v69
	v_and_b32_e32 v15, 0xffff0000, v69
	v_pk_add_f32 v[14:15], v[12:13], v[14:15]
	v_add_f32_e32 v12, v16, v17
	v_add_f32_e32 v12, v14, v12
	v_add_f32_e32 v12, v15, v12
	s_waitcnt lgkmcnt(0)
	v_mov_b32_e32 v32, v31
	s_nop 1
	v_permlane32_swap_b32_e32 v32, v31
	s_nop 1
	v_add_f32_e32 v31, v31, v32
	s_waitcnt lgkmcnt(0)
	v_mov_b32_e32 v13, v70
	s_nop 1
	v_permlane32_swap_b32_e32 v13, v70
	s_nop 1
	v_add_f32_e32 v13, v70, v13
	s_waitcnt lgkmcnt(0)
	v_mov_b32_e32 v32, v12
	s_nop 1
	v_permlane32_swap_b32_e32 v32, v12
	s_nop 1
	v_add_f32_e32 v12, v12, v32
	s_waitcnt lgkmcnt(0)
	v_mov_b32_e32 v32, v13
	s_nop 1
	v_permlane16_swap_b32_e32 v32, v13
	s_nop 1
	v_add_f32_e32 v13, v13, v32
	s_waitcnt lgkmcnt(0)
	v_mov_b32_e32 v32, v26
	s_nop 1
	v_permlane16_swap_b32_e32 v32, v26
	s_nop 1
	v_add_f32_e32 v26, v26, v32
	v_rcp_f32_e32 v101, v100
	s_nop 0
	v_mul_f32_e32 v98, v98, v101
	v_mul_f32_e32 v100, 0xbfb8aa3b, v34
	v_exp_f32_e32 v100, v100
	s_waitcnt lgkmcnt(0)
	v_mov_b32_e32 v32, v27
	s_nop 1
	v_permlane16_swap_b32_e32 v32, v27
	s_nop 1
	v_add_f32_e32 v27, v27, v32
	v_add_f32_e32 v100, 1.0, v100
	s_waitcnt lgkmcnt(0)
	v_mov_b32_e32 v32, v28
	s_nop 1
	v_permlane16_swap_b32_e32 v32, v28
	s_nop 1
	v_add_f32_e32 v28, v28, v32
	s_waitcnt lgkmcnt(0)
	v_mov_b32_e32 v32, v29
	s_nop 1
	v_permlane16_swap_b32_e32 v32, v29
	s_nop 1
	v_add_f32_e32 v29, v29, v32
	s_waitcnt lgkmcnt(0)
	v_mov_b32_e32 v32, v30
	s_nop 1
	v_permlane16_swap_b32_e32 v32, v30
	s_nop 1
	v_add_f32_e32 v30, v30, v32
	s_waitcnt lgkmcnt(0)
	v_mov_b32_e32 v32, v31
	s_nop 1
	v_permlane16_swap_b32_e32 v32, v31
	s_nop 1
	v_add_f32_e32 v31, v31, v32
	v_rcp_f32_e32 v101, v100
	s_nop 0
	v_mul_f32_e32 v100, v34, v101
	v_mul_f32_e32 v34, 0xbfb8aa3b, v99
	v_exp_f32_e32 v34, v34
	s_waitcnt lgkmcnt(0)
	v_mov_b32_e32 v32, v12
	s_nop 1
	v_permlane16_swap_b32_e32 v32, v12
	s_nop 1
	v_add_f32_e32 v12, v12, v32
	v_add_f32_e32 v34, 1.0, v34
	s_waitcnt lgkmcnt(0)
	s_nop 1
	v_add_f32_dpp v13, v13, v13 row_mirror row_mask:0xf bank_mask:0xf
	s_waitcnt lgkmcnt(0)
	s_nop 1
	v_add_f32_dpp v26, v26, v26 row_mirror row_mask:0xf bank_mask:0xf
	s_waitcnt lgkmcnt(0)
	s_nop 1
	v_add_f32_dpp v27, v27, v27 row_mirror row_mask:0xf bank_mask:0xf
	s_waitcnt lgkmcnt(0)
	s_nop 1
	v_add_f32_dpp v28, v28, v28 row_mirror row_mask:0xf bank_mask:0xf
	v_rcp_f32_e32 v101, v34
	s_nop 0
	v_mul_f32_e32 v99, v99, v101
	v_mul_f32_e32 v34, 0xbfb8aa3b, v35
	v_exp_f32_e32 v34, v34
	s_waitcnt lgkmcnt(0)
	s_nop 1
	v_add_f32_dpp v29, v29, v29 row_mirror row_mask:0xf bank_mask:0xf
	v_add_f32_e32 v34, 1.0, v34
	s_waitcnt lgkmcnt(0)
	s_nop 1
	v_add_f32_dpp v30, v30, v30 row_mirror row_mask:0xf bank_mask:0xf
	s_waitcnt lgkmcnt(0)
	s_nop 1
	v_add_f32_dpp v31, v31, v31 row_mirror row_mask:0xf bank_mask:0xf
	s_waitcnt lgkmcnt(0)
	s_nop 1
	v_add_f32_dpp v12, v12, v12 row_mirror row_mask:0xf bank_mask:0xf
	s_waitcnt lgkmcnt(0)
	s_nop 1
	v_add_f32_dpp v13, v13, v13 row_half_mirror row_mask:0xf bank_mask:0xf
	v_rcp_f32_e32 v101, v34
	s_nop 0
	v_mul_f32_e32 v101, v35, v101
	s_waitcnt lgkmcnt(0)
	s_nop 1
	v_add_f32_dpp v26, v26, v26 row_half_mirror row_mask:0xf bank_mask:0xf
	s_waitcnt lgkmcnt(0)
	s_nop 1
	v_add_f32_dpp v27, v27, v27 row_half_mirror row_mask:0xf bank_mask:0xf
	s_waitcnt lgkmcnt(0)
	s_nop 1
	v_add_f32_dpp v28, v28, v28 row_half_mirror row_mask:0xf bank_mask:0xf
	s_waitcnt lgkmcnt(0)
	s_nop 1
	v_add_f32_dpp v29, v29, v29 row_half_mirror row_mask:0xf bank_mask:0xf
	s_waitcnt lgkmcnt(0)
	s_nop 1
	v_add_f32_dpp v30, v30, v30 row_half_mirror row_mask:0xf bank_mask:0xf
	s_waitcnt lgkmcnt(0)
	s_nop 1
	v_add_f32_dpp v31, v31, v31 row_half_mirror row_mask:0xf bank_mask:0xf
	s_waitcnt lgkmcnt(0)
	s_nop 1
	v_add_f32_dpp v12, v12, v12 row_half_mirror row_mask:0xf bank_mask:0xf
	s_waitcnt lgkmcnt(0)
	s_nop 1
	v_add_f32_dpp v13, v13, v13 quad_perm:[2,3,0,1] row_mask:0xf bank_mask:0xf
	s_waitcnt lgkmcnt(0)
	s_nop 1
	v_add_f32_dpp v26, v26, v26 quad_perm:[2,3,0,1] row_mask:0xf bank_mask:0xf
	s_waitcnt lgkmcnt(0)
	s_nop 1
	v_add_f32_dpp v27, v27, v27 quad_perm:[2,3,0,1] row_mask:0xf bank_mask:0xf
	s_waitcnt lgkmcnt(0)
	s_nop 1
	v_add_f32_dpp v28, v28, v28 quad_perm:[2,3,0,1] row_mask:0xf bank_mask:0xf
	s_waitcnt lgkmcnt(0)
	s_nop 1
	v_add_f32_dpp v29, v29, v29 quad_perm:[2,3,0,1] row_mask:0xf bank_mask:0xf
	s_waitcnt lgkmcnt(0)
	s_nop 1
	v_add_f32_dpp v30, v30, v30 quad_perm:[2,3,0,1] row_mask:0xf bank_mask:0xf
	s_waitcnt lgkmcnt(0)
	s_nop 1
	v_add_f32_dpp v31, v31, v31 quad_perm:[2,3,0,1] row_mask:0xf bank_mask:0xf
	s_waitcnt lgkmcnt(0)
	s_nop 1
	v_add_f32_dpp v12, v12, v12 quad_perm:[2,3,0,1] row_mask:0xf bank_mask:0xf
	s_waitcnt lgkmcnt(0)
	s_nop 1
	v_add_f32_dpp v13, v13, v13 quad_perm:[1,0,3,2] row_mask:0xf bank_mask:0xf
	v_fmamk_f32 v5, v13, 0xbb800000, v5
	v_fmac_f32_e32 v4, 0xbb800000, v13
	v_fmamk_f32 v7, v13, 0xbb800000, v7
	v_fmac_f32_e32 v6, 0xbb800000, v13
	s_waitcnt lgkmcnt(0)
	s_nop 1
	v_add_f32_dpp v26, v26, v26 quad_perm:[1,0,3,2] row_mask:0xf bank_mask:0xf
	v_fmamk_f32 v81, v26, 0xbb800000, v81
	v_fmac_f32_e32 v80, 0xbb800000, v26
	v_pk_mul_f32 v[92:93], v[4:5], v[4:5]
	v_fmamk_f32 v79, v26, 0xbb800000, v79
	v_fmac_f32_e32 v78, 0xbb800000, v26
	v_pk_mul_f32 v[96:97], v[80:81], v[80:81]
	v_pk_mul_f32 v[90:91], v[6:7], v[6:7]
	v_pk_mul_f32 v[94:95], v[78:79], v[78:79]
	v_mov_b32_e32 v34, v96
	v_mov_b32_e32 v35, v92
	v_mov_b32_e32 v92, v97
	v_pk_add_f32 v[34:35], v[34:35], v[92:93]
	v_mov_b32_e32 v92, v94
	v_mov_b32_e32 v93, v90
	v_pk_add_f32 v[34:35], v[92:93], v[34:35]
	v_mov_b32_e32 v90, v95
	v_pk_add_f32 v[34:35], v[90:91], v[34:35]
	s_waitcnt lgkmcnt(0)
	v_mov_b32_e32 v90, v34
	v_mov_b32_e32 v91, v35
	s_nop 1
	v_permlane32_swap_b32_e32 v90, v34
	v_permlane32_swap_b32_e32 v91, v35
	s_nop 1
	v_pk_add_f32 v[34:35], v[34:35], v[90:91]
	s_waitcnt lgkmcnt(0)
	s_nop 1
	v_add_f32_dpp v27, v27, v27 quad_perm:[1,0,3,2] row_mask:0xf bank_mask:0xf
	v_fmamk_f32 v65, v27, 0xbb800000, v65
	v_fmac_f32_e32 v64, 0xbb800000, v27
	s_waitcnt lgkmcnt(0)
	v_mov_b32_e32 v90, v34
	v_mov_b32_e32 v91, v35
	s_nop 1
	v_permlane16_swap_b32_e32 v90, v34
	v_permlane16_swap_b32_e32 v91, v35
	s_nop 1
	v_pk_add_f32 v[34:35], v[34:35], v[90:91]
	s_waitcnt lgkmcnt(0)
	s_nop 1
	v_add_f32_dpp v28, v28, v28 quad_perm:[1,0,3,2] row_mask:0xf bank_mask:0xf
	v_fmamk_f32 v61, v28, 0xbb800000, v61
	v_fmac_f32_e32 v60, 0xbb800000, v28
	v_fmamk_f32 v67, v27, 0xbb800000, v67
	s_waitcnt lgkmcnt(0)
	s_nop 1
	v_add_f32_dpp v29, v29, v29 quad_perm:[1,0,3,2] row_mask:0xf bank_mask:0xf
	s_waitcnt lgkmcnt(0)
	s_nop 1
	v_add_f32_dpp v35, v35, v35 row_mirror row_mask:0xf bank_mask:0xf
	v_add_f32_dpp v34, v34, v34 row_mirror row_mask:0xf bank_mask:0xf
	v_fmac_f32_e32 v66, 0xbb800000, v27
	s_waitcnt lgkmcnt(0)
	s_nop 1
	v_add_f32_dpp v30, v30, v30 quad_perm:[1,0,3,2] row_mask:0xf bank_mask:0xf
	v_pk_mul_f32 v[70:71], v[64:65], v[64:65]
	s_waitcnt lgkmcnt(0)
	s_nop 1
	v_add_f32_dpp v35, v35, v35 row_half_mirror row_mask:0xf bank_mask:0xf
	v_add_f32_dpp v34, v34, v34 row_half_mirror row_mask:0xf bank_mask:0xf
	s_waitcnt lgkmcnt(0)
	s_nop 1
	v_add_f32_dpp v31, v31, v31 quad_perm:[1,0,3,2] row_mask:0xf bank_mask:0xf
	v_fmamk_f32 v59, v28, 0xbb800000, v59
	v_fmac_f32_e32 v58, 0xbb800000, v28
	s_waitcnt lgkmcnt(0)
	s_nop 1
	v_add_f32_dpp v35, v35, v35 quad_perm:[2,3,0,1] row_mask:0xf bank_mask:0xf
	v_add_f32_dpp v34, v34, v34 quad_perm:[2,3,0,1] row_mask:0xf bank_mask:0xf
	s_waitcnt lgkmcnt(0)
	s_nop 1
	v_add_f32_dpp v12, v12, v12 quad_perm:[1,0,3,2] row_mask:0xf bank_mask:0xf
	v_fmamk_f32 v17, v12, 0xbb800000, v17
	v_fmac_f32_e32 v16, 0xbb800000, v12
	v_fmamk_f32 v15, v12, 0xbb800000, v15
	v_fmac_f32_e32 v14, 0xbb800000, v12
	v_mad_i64_i32 v[12:13], s[0:1], v82, s70, v[10:11]
	s_mov_b32 s0, 0x358637bd
	s_waitcnt lgkmcnt(0)
	s_nop 1
	v_add_f32_dpp v91, v35, v35 quad_perm:[1,0,3,2] row_mask:0xf bank_mask:0xf
	v_add_f32_dpp v90, v34, v34 quad_perm:[1,0,3,2] row_mask:0xf bank_mask:0xf
	v_mov_b64_e32 v[34:35], s[0:1]
	v_pk_fma_f32 v[90:91], v[90:91], s[34:35], v[34:35] op_sel_hi:[1,0,0]
	v_pk_mul_f32 v[74:75], v[60:61], v[60:61]
	v_mul_f32_e32 v92, 0x4b800000, v91
	v_cmp_gt_f32_e64 s[0:1], s72, v91
	v_cmp_gt_f32_e32 vcc, s72, v90
	v_pk_mul_f32 v[68:69], v[66:67], v[66:67]
	v_cndmask_b32_e64 v91, v91, v92, s[0:1]
	v_rsq_f32_e32 v91, v91
	v_pk_mul_f32 v[72:73], v[58:59], v[58:59]
	v_fmamk_f32 v45, v29, 0xbb800000, v45
	v_fmac_f32_e32 v44, 0xbb800000, v29
	v_mul_f32_e32 v92, 0x45800000, v91
	v_cndmask_b32_e64 v91, v91, v92, s[0:1]
	v_mul_f32_e32 v4, v4, v91
	v_mul_f32_e32 v5, v5, v91
	v_mul_f32_e32 v4, v0, v4
	v_mul_f32_e32 v5, v1, v5
	v_mul_f32_e32 v4, v98, v4
	v_mul_f32_e32 v5, v100, v5
	v_cvt_pk_bf16_f32 v4, v4, v5
	v_mul_f32_e32 v5, v6, v91
	v_mul_f32_e32 v5, v2, v5
	v_mul_f32_e32 v6, v7, v91
	v_mul_f32_e32 v5, v99, v5
	v_mul_f32_e32 v6, v3, v6
	v_mul_f32_e32 v6, v101, v6
	v_cvt_pk_bf16_f32 v5, v5, v6
	global_store_dwordx2 v[12:13], v[4:5], off
	v_mul_f32_e32 v4, 0x4b800000, v90
	v_cndmask_b32_e32 v4, v90, v4, vcc
	v_rsq_f32_e32 v4, v4
	v_lshlrev_b32_e32 v91, 16, v76
	v_and_b32_e32 v76, 0xffff0000, v76
	v_lshlrev_b32_e32 v92, 16, v77
	v_mul_f32_e32 v5, 0x45800000, v4
	v_cndmask_b32_e32 v90, v4, v5, vcc
	ds_read_b128 v[4:7], v83 offset:1024
	v_mul_f32_e32 v80, v80, v90
	v_and_b32_e32 v77, 0xffff0000, v77
	v_fmamk_f32 v41, v30, 0xbb800000, v41
	v_fmac_f32_e32 v40, 0xbb800000, v30
	s_waitcnt lgkmcnt(0)
	v_mul_f32_e32 v4, v80, v4
	v_mul_f32_e32 v80, 0xbfb8aa3b, v91
	v_exp_f32_e32 v80, v80
	v_fmamk_f32 v47, v29, 0xbb800000, v47
	v_fmac_f32_e32 v46, 0xbb800000, v29
	v_pk_mul_f32 v[50:51], v[44:45], v[44:45]
	v_add_f32_e32 v80, 1.0, v80
	v_fmamk_f32 v39, v30, 0xbb800000, v39
	v_fmac_f32_e32 v38, 0xbb800000, v30
	v_pk_mul_f32 v[54:55], v[40:41], v[40:41]
	v_rcp_f32_e32 v93, v80
	s_nop 0
	v_mul_f32_e32 v80, v91, v93
	v_mul_f32_e32 v4, v80, v4
	v_mul_f32_e32 v80, v81, v90
	v_mul_f32_e32 v5, v80, v5
	v_mul_f32_e32 v80, 0xbfb8aa3b, v76
	v_exp_f32_e32 v80, v80
	v_pk_mul_f32 v[48:49], v[46:47], v[46:47]
	v_pk_mul_f32 v[52:53], v[38:39], v[38:39]
	v_fmamk_f32 v23, v31, 0xbb800000, v23
	v_add_f32_e32 v80, 1.0, v80
	v_fmac_f32_e32 v22, 0xbb800000, v31
	v_fmamk_f32 v25, v31, 0xbb800000, v25
	v_fmac_f32_e32 v24, 0xbb800000, v31
	v_rcp_f32_e32 v81, v80
	s_nop 0
	v_mul_f32_e32 v76, v76, v81
	v_mul_f32_e32 v5, v76, v5
	v_cvt_pk_bf16_f32 v4, v4, v5
	v_mul_f32_e32 v5, v78, v90
	v_mul_f32_e32 v5, v5, v6
	v_mul_f32_e32 v6, 0xbfb8aa3b, v92
	v_exp_f32_e32 v6, v6
	v_pk_mul_f32 v[28:29], v[22:23], v[22:23]
	v_pk_mul_f32 v[32:33], v[16:17], v[16:17]
	v_pk_mul_f32 v[26:27], v[24:25], v[24:25]
	v_add_f32_e32 v6, 1.0, v6
	v_pk_mul_f32 v[30:31], v[14:15], v[14:15]
	v_add_u32_e32 v82, s14, v82
	v_rcp_f32_e32 v76, v6
	s_nop 0
	v_mul_f32_e32 v6, v92, v76
	v_mul_f32_e32 v5, v6, v5
	v_mul_f32_e32 v6, v79, v90
	v_mul_f32_e32 v6, v6, v7
	v_mul_f32_e32 v7, 0xbfb8aa3b, v77
	v_exp_f32_e32 v7, v7
	s_nop 0
	v_add_f32_e32 v7, 1.0, v7
	s_nop 0
	v_rcp_f32_e32 v76, v7
	s_nop 0
	v_mul_f32_e32 v7, v77, v76
	v_lshlrev_b32_e32 v76, 16, v62
	v_mul_f32_e32 v78, 0xbfb8aa3b, v76
	v_exp_f32_e32 v78, v78
	v_and_b32_e32 v62, 0xffff0000, v62
	v_lshlrev_b32_e32 v77, 16, v63
	v_and_b32_e32 v63, 0xffff0000, v63
	v_add_f32_e32 v78, 1.0, v78
	v_mul_f32_e32 v6, v7, v6
	v_cvt_pk_bf16_f32 v5, v5, v6
	global_store_dwordx2 v[12:13], v[4:5], off offset:512
	v_rcp_f32_e32 v79, v78
	s_nop 0
	v_mul_f32_e32 v76, v76, v79
	v_mul_f32_e32 v78, 0xbfb8aa3b, v62
	v_exp_f32_e32 v78, v78
	ds_read_b128 v[4:7], v83 offset:2048
	v_add_f32_e32 v78, 1.0, v78
	s_nop 0
	v_rcp_f32_e32 v79, v78
	s_nop 0
	v_mul_f32_e32 v78, v62, v79
	v_mul_f32_e32 v62, 0xbfb8aa3b, v77
	v_exp_f32_e32 v62, v62
	s_nop 0
	v_add_f32_e32 v62, 1.0, v62
	s_nop 0
	v_rcp_f32_e32 v79, v62
	s_nop 0
	v_mul_f32_e32 v77, v77, v79
	v_mul_f32_e32 v62, 0xbfb8aa3b, v63
	v_exp_f32_e32 v62, v62
	s_nop 0
	v_add_f32_e32 v62, 1.0, v62
	s_nop 0
	v_rcp_f32_e32 v79, v62
	s_nop 0
	v_mul_f32_e32 v79, v63, v79
	v_mov_b32_e32 v62, v74
	v_mov_b32_e32 v63, v70
	v_mov_b32_e32 v70, v75
	v_pk_add_f32 v[62:63], v[62:63], v[70:71]
	v_mov_b32_e32 v70, v72
	v_mov_b32_e32 v71, v68
	v_pk_add_f32 v[62:63], v[70:71], v[62:63]
	v_mov_b32_e32 v68, v73
	v_pk_add_f32 v[62:63], v[68:69], v[62:63]
	s_waitcnt lgkmcnt(0)
	v_mov_b32_e32 v68, v62
	v_mov_b32_e32 v69, v63
	s_nop 1
	v_permlane32_swap_b32_e32 v68, v62
	v_permlane32_swap_b32_e32 v69, v63
	s_nop 1
	v_pk_add_f32 v[62:63], v[62:63], v[68:69]
	s_waitcnt lgkmcnt(0)
	v_mov_b32_e32 v68, v62
	v_mov_b32_e32 v69, v63
	s_nop 1
	v_permlane16_swap_b32_e32 v68, v62
	v_permlane16_swap_b32_e32 v69, v63
	s_nop 1
	v_pk_add_f32 v[62:63], v[62:63], v[68:69]
	s_waitcnt lgkmcnt(0)
	s_nop 1
	v_add_f32_dpp v63, v63, v63 row_mirror row_mask:0xf bank_mask:0xf
	v_add_f32_dpp v62, v62, v62 row_mirror row_mask:0xf bank_mask:0xf
	s_waitcnt lgkmcnt(0)
	s_nop 1
	v_add_f32_dpp v63, v63, v63 row_half_mirror row_mask:0xf bank_mask:0xf
	v_add_f32_dpp v62, v62, v62 row_half_mirror row_mask:0xf bank_mask:0xf
	s_waitcnt lgkmcnt(0)
	s_nop 1
	v_add_f32_dpp v63, v63, v63 quad_perm:[2,3,0,1] row_mask:0xf bank_mask:0xf
	v_add_f32_dpp v62, v62, v62 quad_perm:[2,3,0,1] row_mask:0xf bank_mask:0xf
	s_waitcnt lgkmcnt(0)
	s_nop 1
	v_add_f32_dpp v63, v63, v63 quad_perm:[1,0,3,2] row_mask:0xf bank_mask:0xf
	v_add_f32_dpp v62, v62, v62 quad_perm:[1,0,3,2] row_mask:0xf bank_mask:0xf
	s_nop 0
	v_pk_fma_f32 v[62:63], v[62:63], s[34:35], v[34:35] op_sel_hi:[1,0,0]
	s_nop 0
	v_mul_f32_e32 v68, 0x4b800000, v63
	v_cmp_gt_f32_e64 s[0:1], s72, v63
	v_cmp_gt_f32_e32 vcc, s72, v62
	s_nop 0
	v_cndmask_b32_e64 v63, v63, v68, s[0:1]
	v_rsq_f32_e32 v63, v63
	s_nop 0
	v_mul_f32_e32 v68, 0x45800000, v63
	v_cndmask_b32_e64 v63, v63, v68, s[0:1]
	v_mul_f32_e32 v64, v64, v63
	v_mul_f32_e32 v4, v64, v4
	v_mul_f32_e32 v64, v65, v63
	v_mul_f32_e32 v5, v64, v5
	v_mul_f32_e32 v4, v76, v4
	v_mul_f32_e32 v5, v78, v5
	v_cvt_pk_bf16_f32 v4, v4, v5
	v_mul_f32_e32 v5, v66, v63
	v_mul_f32_e32 v5, v5, v6
	v_mul_f32_e32 v6, v67, v63
	v_mul_f32_e32 v5, v77, v5
	v_mul_f32_e32 v6, v6, v7
	v_mul_f32_e32 v6, v79, v6
	v_cvt_pk_bf16_f32 v5, v5, v6
	global_store_dwordx2 v[12:13], v[4:5], off offset:1024
	v_mul_f32_e32 v4, 0x4b800000, v62
	v_cndmask_b32_e32 v4, v62, v4, vcc
	v_rsq_f32_e32 v4, v4
	v_lshlrev_b32_e32 v63, 16, v56
	v_and_b32_e32 v56, 0xffff0000, v56
	v_lshlrev_b32_e32 v64, 16, v57
	v_mul_f32_e32 v5, 0x45800000, v4
	v_cndmask_b32_e32 v62, v4, v5, vcc
	ds_read_b128 v[4:7], v83 offset:3072
	v_mul_f32_e32 v60, v60, v62
	v_and_b32_e32 v57, 0xffff0000, v57
	s_waitcnt lgkmcnt(0)
	v_mul_f32_e32 v4, v60, v4
	v_mul_f32_e32 v60, 0xbfb8aa3b, v63
	v_exp_f32_e32 v60, v60
	s_nop 0
	v_add_f32_e32 v60, 1.0, v60
	s_nop 0
	v_rcp_f32_e32 v65, v60
	s_nop 0
	v_mul_f32_e32 v60, v63, v65
	v_mul_f32_e32 v4, v60, v4
	v_mul_f32_e32 v60, v61, v62
	v_mul_f32_e32 v5, v60, v5
	v_mul_f32_e32 v60, 0xbfb8aa3b, v56
	v_exp_f32_e32 v60, v60
	s_nop 0
	v_add_f32_e32 v60, 1.0, v60
	s_nop 0
	v_rcp_f32_e32 v61, v60
	s_nop 0
	v_mul_f32_e32 v56, v56, v61
	v_mul_f32_e32 v5, v56, v5
	v_cvt_pk_bf16_f32 v4, v4, v5
	v_mul_f32_e32 v5, v58, v62
	v_mul_f32_e32 v5, v5, v6
	v_mul_f32_e32 v6, 0xbfb8aa3b, v64
	v_exp_f32_e32 v6, v6
	s_nop 0
	v_add_f32_e32 v6, 1.0, v6
	s_nop 0
	v_rcp_f32_e32 v56, v6
	s_nop 0
	v_mul_f32_e32 v6, v64, v56
	v_mul_f32_e32 v5, v6, v5
	v_mul_f32_e32 v6, v59, v62
	v_mul_f32_e32 v6, v6, v7
	v_mul_f32_e32 v7, 0xbfb8aa3b, v57
	v_exp_f32_e32 v7, v7
	s_nop 0
	v_add_f32_e32 v7, 1.0, v7
	s_nop 0
	v_rcp_f32_e32 v56, v7
	s_nop 0
	v_mul_f32_e32 v7, v57, v56
	v_lshlrev_b32_e32 v56, 16, v42
	v_mul_f32_e32 v58, 0xbfb8aa3b, v56
	v_exp_f32_e32 v58, v58
	v_and_b32_e32 v42, 0xffff0000, v42
	v_lshlrev_b32_e32 v57, 16, v43
	v_and_b32_e32 v43, 0xffff0000, v43
	v_add_f32_e32 v58, 1.0, v58
	v_mul_f32_e32 v6, v7, v6
	v_cvt_pk_bf16_f32 v5, v5, v6
	global_store_dwordx2 v[12:13], v[4:5], off offset:1536
	v_rcp_f32_e32 v59, v58
	s_nop 0
	v_mul_f32_e32 v56, v56, v59
	v_mul_f32_e32 v58, 0xbfb8aa3b, v42
	v_exp_f32_e32 v58, v58
	ds_read_b128 v[4:7], v83 offset:4096
	v_add_f32_e32 v58, 1.0, v58
	s_nop 0
	v_rcp_f32_e32 v59, v58
	s_nop 0
	v_mul_f32_e32 v58, v42, v59
	v_mul_f32_e32 v42, 0xbfb8aa3b, v57
	v_exp_f32_e32 v42, v42
	s_nop 0
	v_add_f32_e32 v42, 1.0, v42
	s_nop 0
	v_rcp_f32_e32 v59, v42
	s_nop 0
	v_mul_f32_e32 v57, v57, v59
	v_mul_f32_e32 v42, 0xbfb8aa3b, v43
	v_exp_f32_e32 v42, v42
	s_nop 0
	v_add_f32_e32 v42, 1.0, v42
	s_nop 0
	v_rcp_f32_e32 v59, v42
	s_nop 0
	v_mul_f32_e32 v59, v43, v59
	v_mov_b32_e32 v42, v54
	v_mov_b32_e32 v43, v50
	v_mov_b32_e32 v50, v55
	v_pk_add_f32 v[42:43], v[42:43], v[50:51]
	v_mov_b32_e32 v50, v52
	v_mov_b32_e32 v51, v48
	v_pk_add_f32 v[42:43], v[50:51], v[42:43]
	v_mov_b32_e32 v48, v53
	v_pk_add_f32 v[42:43], v[48:49], v[42:43]
	s_waitcnt lgkmcnt(0)
	v_mov_b32_e32 v48, v42
	v_mov_b32_e32 v49, v43
	s_nop 1
	v_permlane32_swap_b32_e32 v48, v42
	v_permlane32_swap_b32_e32 v49, v43
	s_nop 1
	v_pk_add_f32 v[42:43], v[42:43], v[48:49]
	s_waitcnt lgkmcnt(0)
	v_mov_b32_e32 v48, v42
	v_mov_b32_e32 v49, v43
	s_nop 1
	v_permlane16_swap_b32_e32 v48, v42
	v_permlane16_swap_b32_e32 v49, v43
	s_nop 1
	v_pk_add_f32 v[42:43], v[42:43], v[48:49]
	s_waitcnt lgkmcnt(0)
	s_nop 1
	v_add_f32_dpp v43, v43, v43 row_mirror row_mask:0xf bank_mask:0xf
	v_add_f32_dpp v42, v42, v42 row_mirror row_mask:0xf bank_mask:0xf
	s_waitcnt lgkmcnt(0)
	s_nop 1
	v_add_f32_dpp v43, v43, v43 row_half_mirror row_mask:0xf bank_mask:0xf
	v_add_f32_dpp v42, v42, v42 row_half_mirror row_mask:0xf bank_mask:0xf
	s_waitcnt lgkmcnt(0)
	s_nop 1
	v_add_f32_dpp v43, v43, v43 quad_perm:[2,3,0,1] row_mask:0xf bank_mask:0xf
	v_add_f32_dpp v42, v42, v42 quad_perm:[2,3,0,1] row_mask:0xf bank_mask:0xf
	s_waitcnt lgkmcnt(0)
	s_nop 1
	v_add_f32_dpp v43, v43, v43 quad_perm:[1,0,3,2] row_mask:0xf bank_mask:0xf
	v_add_f32_dpp v42, v42, v42 quad_perm:[1,0,3,2] row_mask:0xf bank_mask:0xf
	s_nop 0
	v_pk_fma_f32 v[42:43], v[42:43], s[34:35], v[34:35] op_sel_hi:[1,0,0]
	s_nop 0
	v_mul_f32_e32 v48, 0x4b800000, v43
	v_cmp_gt_f32_e64 s[0:1], s72, v43
	v_cmp_gt_f32_e32 vcc, s72, v42
	s_nop 0
	v_cndmask_b32_e64 v43, v43, v48, s[0:1]
	v_rsq_f32_e32 v43, v43
	s_nop 0
	v_mul_f32_e32 v48, 0x45800000, v43
	v_cndmask_b32_e64 v43, v43, v48, s[0:1]
	v_mul_f32_e32 v44, v44, v43
	v_mul_f32_e32 v4, v44, v4
	v_mul_f32_e32 v44, v45, v43
	v_mul_f32_e32 v5, v44, v5
	v_mul_f32_e32 v4, v56, v4
	v_mul_f32_e32 v5, v58, v5
	v_cvt_pk_bf16_f32 v4, v4, v5
	v_mul_f32_e32 v5, v46, v43
	v_mul_f32_e32 v5, v5, v6
	v_mul_f32_e32 v6, v47, v43
	v_mul_f32_e32 v5, v57, v5
	v_mul_f32_e32 v6, v6, v7
	v_mul_f32_e32 v6, v59, v6
	v_cvt_pk_bf16_f32 v5, v5, v6
	global_store_dwordx2 v[12:13], v[4:5], off offset:2048
	v_mul_f32_e32 v4, 0x4b800000, v42
	v_cndmask_b32_e32 v4, v42, v4, vcc
	v_rsq_f32_e32 v4, v4
	v_lshlrev_b32_e32 v43, 16, v36
	v_and_b32_e32 v36, 0xffff0000, v36
	v_lshlrev_b32_e32 v44, 16, v37
	v_mul_f32_e32 v5, 0x45800000, v4
	v_cndmask_b32_e32 v42, v4, v5, vcc
	ds_read_b128 v[4:7], v83 offset:5120
	v_mul_f32_e32 v40, v40, v42
	v_and_b32_e32 v37, 0xffff0000, v37
	s_waitcnt lgkmcnt(0)
	v_mul_f32_e32 v4, v40, v4
	v_mul_f32_e32 v40, 0xbfb8aa3b, v43
	v_exp_f32_e32 v40, v40
	s_nop 0
	v_add_f32_e32 v40, 1.0, v40
	s_nop 0
	v_rcp_f32_e32 v45, v40
	s_nop 0
	v_mul_f32_e32 v40, v43, v45
	v_mul_f32_e32 v4, v40, v4
	v_mul_f32_e32 v40, v41, v42
	v_mul_f32_e32 v5, v40, v5
	v_mul_f32_e32 v40, 0xbfb8aa3b, v36
	v_exp_f32_e32 v40, v40
	s_nop 0
	v_add_f32_e32 v40, 1.0, v40
	s_nop 0
	v_rcp_f32_e32 v41, v40
	s_nop 0
	v_mul_f32_e32 v36, v36, v41
	v_mul_f32_e32 v5, v36, v5
	v_cvt_pk_bf16_f32 v4, v4, v5
	v_mul_f32_e32 v5, v38, v42
	v_mul_f32_e32 v5, v5, v6
	v_mul_f32_e32 v6, 0xbfb8aa3b, v44
	v_exp_f32_e32 v6, v6
	s_nop 0
	v_add_f32_e32 v6, 1.0, v6
	s_nop 0
	v_rcp_f32_e32 v36, v6
	s_nop 0
	v_mul_f32_e32 v6, v44, v36
	v_mul_f32_e32 v5, v6, v5
	v_mul_f32_e32 v6, v39, v42
	v_mul_f32_e32 v6, v6, v7
	v_mul_f32_e32 v7, 0xbfb8aa3b, v37
	v_exp_f32_e32 v7, v7
	s_nop 0
	v_add_f32_e32 v7, 1.0, v7
	s_nop 0
	v_rcp_f32_e32 v36, v7
	s_nop 0
	v_mul_f32_e32 v7, v37, v36
	v_lshlrev_b32_e32 v36, 16, v20
	v_mul_f32_e32 v38, 0xbfb8aa3b, v36
	v_exp_f32_e32 v38, v38
	v_and_b32_e32 v20, 0xffff0000, v20
	v_lshlrev_b32_e32 v37, 16, v21
	v_and_b32_e32 v21, 0xffff0000, v21
	v_add_f32_e32 v38, 1.0, v38
	v_mul_f32_e32 v6, v7, v6
	v_cvt_pk_bf16_f32 v5, v5, v6
	global_store_dwordx2 v[12:13], v[4:5], off offset:2560
	v_rcp_f32_e32 v39, v38
	s_nop 0
	v_mul_f32_e32 v36, v36, v39
	v_mul_f32_e32 v38, 0xbfb8aa3b, v20
	v_exp_f32_e32 v38, v38
	ds_read_b128 v[4:7], v83 offset:6144
	v_add_f32_e32 v38, 1.0, v38
	s_nop 0
	v_rcp_f32_e32 v39, v38
	s_nop 0
	v_mul_f32_e32 v38, v20, v39
	v_mul_f32_e32 v20, 0xbfb8aa3b, v37
	v_exp_f32_e32 v20, v20
	s_nop 0
	v_add_f32_e32 v20, 1.0, v20
	s_nop 0
	v_rcp_f32_e32 v39, v20
	s_nop 0
	v_mul_f32_e32 v37, v37, v39
	v_mul_f32_e32 v20, 0xbfb8aa3b, v21
	v_exp_f32_e32 v20, v20
	s_nop 0
	v_add_f32_e32 v20, 1.0, v20
	s_nop 0
	v_rcp_f32_e32 v39, v20
	s_nop 0
	v_mul_f32_e32 v39, v21, v39
	v_mov_b32_e32 v20, v32
	v_mov_b32_e32 v21, v28
	v_mov_b32_e32 v28, v33
	v_pk_add_f32 v[20:21], v[20:21], v[28:29]
	v_mov_b32_e32 v28, v30
	v_mov_b32_e32 v29, v26
	v_pk_add_f32 v[20:21], v[28:29], v[20:21]
	v_mov_b32_e32 v26, v31
	v_pk_add_f32 v[20:21], v[26:27], v[20:21]
	s_waitcnt lgkmcnt(0)
	v_mov_b32_e32 v26, v20
	v_mov_b32_e32 v27, v21
	s_nop 1
	v_permlane32_swap_b32_e32 v26, v20
	v_permlane32_swap_b32_e32 v27, v21
	s_nop 1
	v_pk_add_f32 v[20:21], v[20:21], v[26:27]
	s_waitcnt lgkmcnt(0)
	v_mov_b32_e32 v26, v20
	v_mov_b32_e32 v27, v21
	s_nop 1
	v_permlane16_swap_b32_e32 v26, v20
	v_permlane16_swap_b32_e32 v27, v21
	s_nop 1
	v_pk_add_f32 v[20:21], v[20:21], v[26:27]
	s_waitcnt lgkmcnt(0)
	s_nop 1
	v_add_f32_dpp v21, v21, v21 row_mirror row_mask:0xf bank_mask:0xf
	v_add_f32_dpp v20, v20, v20 row_mirror row_mask:0xf bank_mask:0xf
	s_waitcnt lgkmcnt(0)
	s_nop 1
	v_add_f32_dpp v21, v21, v21 row_half_mirror row_mask:0xf bank_mask:0xf
	v_add_f32_dpp v20, v20, v20 row_half_mirror row_mask:0xf bank_mask:0xf
	s_waitcnt lgkmcnt(0)
	s_nop 1
	v_add_f32_dpp v21, v21, v21 quad_perm:[2,3,0,1] row_mask:0xf bank_mask:0xf
	v_add_f32_dpp v20, v20, v20 quad_perm:[2,3,0,1] row_mask:0xf bank_mask:0xf
	s_waitcnt lgkmcnt(0)
	s_nop 1
	v_add_f32_dpp v21, v21, v21 quad_perm:[1,0,3,2] row_mask:0xf bank_mask:0xf
	v_add_f32_dpp v20, v20, v20 quad_perm:[1,0,3,2] row_mask:0xf bank_mask:0xf
	s_nop 0
	v_pk_fma_f32 v[20:21], v[20:21], s[34:35], v[34:35] op_sel_hi:[1,0,0]
	s_nop 0
	v_mul_f32_e32 v26, 0x4b800000, v21
	v_cmp_gt_f32_e64 s[0:1], s72, v21
	v_cmp_gt_f32_e32 vcc, s72, v20
	s_nop 0
	v_cndmask_b32_e64 v21, v21, v26, s[0:1]
	v_rsq_f32_e32 v21, v21
	s_nop 0
	v_mul_f32_e32 v26, 0x45800000, v21
	v_cndmask_b32_e64 v21, v21, v26, s[0:1]
	v_mul_f32_e32 v22, v22, v21
	v_mul_f32_e32 v4, v22, v4
	v_mul_f32_e32 v22, v23, v21
	v_mul_f32_e32 v5, v22, v5
	v_mul_f32_e32 v4, v36, v4
	v_mul_f32_e32 v5, v38, v5
	v_cvt_pk_bf16_f32 v4, v4, v5
	v_mul_f32_e32 v5, v24, v21
	v_mul_f32_e32 v5, v5, v6
	v_mul_f32_e32 v6, v25, v21
	v_mul_f32_e32 v5, v37, v5
	v_mul_f32_e32 v6, v6, v7
	v_mul_f32_e32 v6, v39, v6
	v_cvt_pk_bf16_f32 v5, v5, v6
	global_store_dwordx2 v[12:13], v[4:5], off offset:3072
	v_mul_f32_e32 v4, 0x4b800000, v20
	v_cndmask_b32_e32 v4, v20, v4, vcc
	v_rsq_f32_e32 v4, v4
	v_lshlrev_b32_e32 v21, 16, v18
	v_and_b32_e32 v22, 0xffff0000, v18
	v_lshlrev_b32_e32 v23, 16, v19
	v_mul_f32_e32 v5, 0x45800000, v4
	v_cndmask_b32_e32 v20, v4, v5, vcc
	ds_read_b128 v[4:7], v83 offset:7168
	v_mul_f32_e32 v16, v16, v20
	v_and_b32_e32 v18, 0xffff0000, v19
	s_waitcnt lgkmcnt(0)
	v_mul_f32_e32 v4, v16, v4
	v_mul_f32_e32 v16, 0xbfb8aa3b, v21
	v_exp_f32_e32 v16, v16
	s_nop 0
	v_add_f32_e32 v16, 1.0, v16
	s_nop 0
	v_rcp_f32_e32 v19, v16
	s_nop 0
	v_mul_f32_e32 v16, v21, v19
	v_mul_f32_e32 v4, v16, v4
	v_mul_f32_e32 v16, v17, v20
	v_mul_f32_e32 v5, v16, v5
	v_mul_f32_e32 v16, 0xbfb8aa3b, v22
	v_exp_f32_e32 v16, v16
	s_nop 0
	v_add_f32_e32 v16, 1.0, v16
	s_nop 0
	v_rcp_f32_e32 v17, v16
	s_nop 0
	v_mul_f32_e32 v16, v22, v17
	v_mul_f32_e32 v5, v16, v5
	v_cvt_pk_bf16_f32 v4, v4, v5
	v_mul_f32_e32 v5, v14, v20
	v_mul_f32_e32 v5, v5, v6
	v_mul_f32_e32 v6, 0xbfb8aa3b, v23
	v_exp_f32_e32 v6, v6
	s_nop 0
	v_add_f32_e32 v6, 1.0, v6
	s_nop 0
	v_rcp_f32_e32 v14, v6
	s_nop 0
	v_mul_f32_e32 v6, v23, v14
	v_mul_f32_e32 v5, v6, v5
	v_mul_f32_e32 v6, v15, v20
	v_mul_f32_e32 v6, v6, v7
	v_mul_f32_e32 v7, 0xbfb8aa3b, v18
	v_exp_f32_e32 v7, v7
	s_nop 0
	v_add_f32_e32 v7, 1.0, v7
	s_movk_i32 s0, 0x1fff
	v_cmp_lt_i32_e32 vcc, s0, v82
	v_rcp_f32_e32 v14, v7
	s_nop 0
	v_mul_f32_e32 v7, v18, v14
	s_or_b64 s[6:7], vcc, s[6:7]
	v_mul_f32_e32 v6, v7, v6
	v_cvt_pk_bf16_f32 v5, v5, v6
	global_store_dwordx2 v[12:13], v[4:5], off offset:3584
	s_andn2_b64 exec, exec, s[6:7]
	s_cbranch_execnz .LBB0_503
